# ret_r3 output gating: the four gate rows fetched together before the gate/silu/store rounds
# baseline (speedup 1.0000x reference)
.LBB0_886:
	s_or_b64 exec, exec, s[6:7]
	s_lshl_b32 s0, s28, 2
	s_add_u32 s0, s22, s0
	s_waitcnt lgkmcnt(0)
	s_addc_u32 s1, s23, 0
	v_lshlrev_b32_e32 v32, 2, v65
	global_load_dword v39, v32, s[0:1]
	global_load_dword v38, v32, s[0:1] offset:64
	global_load_dword v37, v32, s[0:1] offset:128
	global_load_dword v36, v32, s[0:1] offset:192
	global_load_dword v35, v32, s[0:1] offset:256
	global_load_dword v34, v32, s[0:1] offset:320
	global_load_dword v33, v32, s[0:1] offset:384
	s_nop 0
	global_load_dword v32, v32, s[0:1] offset:448
	v_add_f32_e32 v40, 0, v4
	v_add_f32_e32 v40, v0, v40
	v_add_f32_e32 v40, v16, v40
	v_add_f32_e32 v40, v28, v40
	v_add_f32_e32 v40, v12, v40
	v_add_f32_e32 v40, v24, v40
	v_add_f32_e32 v40, v8, v40
	v_add_f32_e32 v40, v20, v40
	v_mov_b32_e32 v42, v28
	v_mov_b32_e32 v43, v16
	v_add_f32_dpp v40, v40, v40 quad_perm:[1,0,3,2] row_mask:0xf bank_mask:0xf bound_ctrl:1
	v_lshlrev_b32_e32 v144, 4, v65
	s_lshl_b32 s80, s28, 1
	v_add_f32_dpp v40, v40, v40 quad_perm:[2,3,0,1] row_mask:0xf bank_mask:0xf bound_ctrl:1
	s_add_u32 s0, s24, s80
	s_addc_u32 s1, s25, 0
	v_add_f32_dpp v40, v40, v40 row_half_mirror row_mask:0xf bank_mask:0xf bound_ctrl:1
	s_add_i32 s26, s26, s40
	s_add_u32 s16, s16, s82
	v_add_f32_dpp v41, v40, v40 row_mirror row_mask:0xf bank_mask:0xf bound_ctrl:1
	v_fmac_f32_e32 v0, 0xbc000000, v41
	v_mul_f32_e32 v40, 0x3c000000, v41
	v_fmac_f32_e32 v4, 0xbc000000, v41
	v_mul_f32_e32 v41, v0, v0
	v_fmac_f32_e32 v41, v4, v4
	v_pk_add_f32 v[42:43], v[42:43], v[40:41] op_sel_hi:[1,0] neg_lo:[0,1] neg_hi:[0,1]
	s_addc_u32 s17, s17, s83
	v_pk_mul_f32 v[44:45], v[42:43], v[42:43]
	s_cmpk_gt_i32 s26, 0x1ff
	v_add_f32_e32 v16, v45, v41
	v_add_f32_e32 v16, v44, v16
	v_mov_b32_e32 v44, v24
	v_mov_b32_e32 v45, v12
	v_pk_add_f32 v[44:45], v[44:45], v[40:41] op_sel_hi:[1,0] neg_lo:[0,1] neg_hi:[0,1]
	s_nop 0
	v_pk_mul_f32 v[46:47], v[44:45], v[44:45]
	s_nop 0
	v_add_f32_e32 v12, v47, v16
	v_add_f32_e32 v12, v46, v12
	v_mov_b32_e32 v46, v20
	v_mov_b32_e32 v47, v8
	v_pk_add_f32 v[40:41], v[46:47], v[40:41] op_sel_hi:[1,0] neg_lo:[0,1] neg_hi:[0,1]
	v_mov_b32_e32 v16, v29
	v_pk_mul_f32 v[46:47], v[40:41], v[40:41]
	s_nop 0
	v_add_f32_e32 v8, v47, v12
	v_add_f32_e32 v8, v46, v8
	s_nop 1
	v_add_f32_dpp v8, v8, v8 quad_perm:[1,0,3,2] row_mask:0xf bank_mask:0xf bound_ctrl:1
	s_nop 1
	v_add_f32_dpp v8, v8, v8 quad_perm:[2,3,0,1] row_mask:0xf bank_mask:0xf bound_ctrl:1
	s_nop 1
	v_add_f32_dpp v8, v8, v8 row_half_mirror row_mask:0xf bank_mask:0xf bound_ctrl:1
	s_nop 1
	v_add_f32_dpp v8, v8, v8 row_mirror row_mask:0xf bank_mask:0xf bound_ctrl:1
	v_fmamk_f32 v8, v8, 0x3c000000, v237
	v_cmp_gt_f32_e32 vcc, s74, v8
	v_mul_f32_e32 v12, 0x4b800000, v8
	s_nop 0
	v_cndmask_b32_e32 v8, v8, v12, vcc
	v_rsq_f32_e32 v8, v8
	s_nop 0
	v_mul_f32_e32 v12, 0x45800000, v8
	v_cndmask_b32_e32 v8, v8, v12, vcc
	v_mul_f32_e32 v4, v4, v8
	v_mul_f32_e32 v0, v0, v8
	s_waitcnt vmcnt(7)
	v_mul_f32_e32 v4, v39, v4
	s_waitcnt vmcnt(6)
	v_mul_f32_e32 v0, v38, v0
	v_cvt_pk_bf16_f32 v4, v4, v145
	ds_write_b16 v60, v4
	v_cvt_pk_bf16_f32 v0, v0, v145
	ds_write_b16 v60, v0 offset:32
	v_mul_f32_e32 v0, v43, v8
	s_waitcnt vmcnt(5)
	v_mul_f32_e32 v0, v37, v0
	v_cvt_pk_bf16_f32 v0, v0, v145
	ds_write_b16 v60, v0 offset:64
	v_mul_f32_e32 v0, v42, v8
	s_waitcnt vmcnt(4)
	v_mul_f32_e32 v0, v36, v0
	v_cvt_pk_bf16_f32 v0, v0, v145
	ds_write_b16 v60, v0 offset:96
	v_mul_f32_e32 v0, v45, v8
	s_waitcnt vmcnt(3)
	v_mul_f32_e32 v0, v35, v0
	v_cvt_pk_bf16_f32 v0, v0, v145
	ds_write_b16 v60, v0 offset:128
	v_mul_f32_e32 v0, v44, v8
	s_waitcnt vmcnt(2)
	v_mul_f32_e32 v0, v34, v0
	v_cvt_pk_bf16_f32 v0, v0, v145
	ds_write_b16 v60, v0 offset:160
	v_mul_f32_e32 v0, v41, v8
	s_waitcnt vmcnt(1)
	v_mul_f32_e32 v0, v33, v0
	v_cvt_pk_bf16_f32 v0, v0, v145
	ds_write_b16 v60, v0 offset:192
	v_mul_f32_e32 v0, v40, v8
	s_waitcnt vmcnt(0)
	v_mul_f32_e32 v0, v32, v0
	v_cvt_pk_bf16_f32 v0, v0, v145
	ds_write_b16 v60, v0 offset:224
	v_add_f32_e32 v0, 0, v5
	v_add_f32_e32 v0, v1, v0
	v_add_f32_e32 v0, v17, v0
	v_add_f32_e32 v0, v29, v0
	v_add_f32_e32 v0, v13, v0
	v_add_f32_e32 v0, v25, v0
	v_add_f32_e32 v0, v9, v0
	v_add_f32_e32 v0, v21, v0
	v_mov_b32_e32 v12, v25
	v_mov_b32_e32 v8, v21
	v_add_f32_dpp v0, v0, v0 quad_perm:[1,0,3,2] row_mask:0xf bank_mask:0xf bound_ctrl:1
	s_nop 1
	v_add_f32_dpp v0, v0, v0 quad_perm:[2,3,0,1] row_mask:0xf bank_mask:0xf bound_ctrl:1
	s_nop 1
	v_add_f32_dpp v0, v0, v0 row_half_mirror row_mask:0xf bank_mask:0xf bound_ctrl:1
	s_nop 1
	v_add_f32_dpp v4, v0, v0 row_mirror row_mask:0xf bank_mask:0xf bound_ctrl:1
	v_mul_f32_e32 v0, 0x3c000000, v4
	v_fmac_f32_e32 v1, 0xbc000000, v4
	v_fmac_f32_e32 v5, 0xbc000000, v4
	v_mul_f32_e32 v4, v1, v1
	v_pk_add_f32 v[16:17], v[16:17], v[0:1] op_sel_hi:[1,0] neg_lo:[0,1] neg_hi:[0,1]
	v_fmac_f32_e32 v4, v5, v5
	v_pk_mul_f32 v[28:29], v[16:17], v[16:17]
	v_pk_add_f32 v[12:13], v[12:13], v[0:1] op_sel_hi:[1,0] neg_lo:[0,1] neg_hi:[0,1]
	v_add_f32_e32 v4, v29, v4
	v_add_f32_e32 v4, v28, v4
	v_pk_mul_f32 v[24:25], v[12:13], v[12:13]
	v_pk_add_f32 v[8:9], v[8:9], v[0:1] op_sel_hi:[1,0] neg_lo:[0,1] neg_hi:[0,1]
	v_add_f32_e32 v4, v25, v4
	v_add_f32_e32 v4, v24, v4
	v_pk_mul_f32 v[20:21], v[8:9], v[8:9]
	s_nop 0
	v_add_f32_e32 v0, v21, v4
	v_add_f32_e32 v0, v20, v0
	s_nop 1
	v_add_f32_dpp v0, v0, v0 quad_perm:[1,0,3,2] row_mask:0xf bank_mask:0xf bound_ctrl:1
	s_nop 1
	v_add_f32_dpp v0, v0, v0 quad_perm:[2,3,0,1] row_mask:0xf bank_mask:0xf bound_ctrl:1
	s_nop 1
	v_add_f32_dpp v0, v0, v0 row_half_mirror row_mask:0xf bank_mask:0xf bound_ctrl:1
	s_nop 1
	v_add_f32_dpp v0, v0, v0 row_mirror row_mask:0xf bank_mask:0xf bound_ctrl:1
	v_fmamk_f32 v0, v0, 0x3c000000, v237
	v_cmp_gt_f32_e32 vcc, s74, v0
	v_mul_f32_e32 v4, 0x4b800000, v0
	s_nop 0
	v_cndmask_b32_e32 v0, v0, v4, vcc
	v_rsq_f32_e32 v0, v0
	s_nop 0
	v_mul_f32_e32 v4, 0x45800000, v0
	v_cndmask_b32_e32 v0, v0, v4, vcc
	v_mul_f32_e32 v4, v5, v0
	v_mul_f32_e32 v1, v1, v0
	v_mul_f32_e32 v4, v39, v4
	v_mul_f32_e32 v1, v38, v1
	v_cvt_pk_bf16_f32 v4, v4, v145
	ds_write_b16 v60, v4 offset:272
	v_cvt_pk_bf16_f32 v1, v1, v145
	ds_write_b16 v60, v1 offset:304
	v_mul_f32_e32 v1, v17, v0
	v_mul_f32_e32 v1, v37, v1
	v_cvt_pk_bf16_f32 v1, v1, v145
	ds_write_b16 v60, v1 offset:336
	v_mul_f32_e32 v1, v16, v0
	v_mul_f32_e32 v1, v36, v1
	v_cvt_pk_bf16_f32 v1, v1, v145
	ds_write_b16 v60, v1 offset:368
	v_mul_f32_e32 v1, v13, v0
	v_mul_f32_e32 v1, v35, v1
	v_cvt_pk_bf16_f32 v1, v1, v145
	ds_write_b16 v60, v1 offset:400
	v_mul_f32_e32 v1, v12, v0
	v_mul_f32_e32 v1, v34, v1
	v_cvt_pk_bf16_f32 v1, v1, v145
	ds_write_b16 v60, v1 offset:432
	v_mul_f32_e32 v1, v9, v0
	v_mul_f32_e32 v0, v8, v0
	v_mul_f32_e32 v1, v33, v1
	v_mul_f32_e32 v0, v32, v0
	v_cvt_pk_bf16_f32 v1, v1, v145
	ds_write_b16 v60, v1 offset:464
	v_cvt_pk_bf16_f32 v0, v0, v145
	ds_write_b16 v60, v0 offset:496
	v_add_f32_e32 v0, 0, v6
	v_add_f32_e32 v0, v2, v0
	v_add_f32_e32 v0, v18, v0
	v_add_f32_e32 v0, v30, v0
	v_add_f32_e32 v0, v14, v0
	v_add_f32_e32 v0, v26, v0
	v_add_f32_e32 v0, v10, v0
	v_add_f32_e32 v0, v22, v0
	v_mov_b32_e32 v4, v30
	v_mov_b32_e32 v5, v18
	v_add_f32_dpp v0, v0, v0 quad_perm:[1,0,3,2] row_mask:0xf bank_mask:0xf bound_ctrl:1
	v_mov_b32_e32 v18, v31
	s_nop 0
	v_add_f32_dpp v0, v0, v0 quad_perm:[2,3,0,1] row_mask:0xf bank_mask:0xf bound_ctrl:1
	s_nop 1
	v_add_f32_dpp v0, v0, v0 row_half_mirror row_mask:0xf bank_mask:0xf bound_ctrl:1
	s_nop 1
	v_add_f32_dpp v1, v0, v0 row_mirror row_mask:0xf bank_mask:0xf bound_ctrl:1
	v_fmac_f32_e32 v2, 0xbc000000, v1
	v_mul_f32_e32 v0, 0x3c000000, v1
	v_fmac_f32_e32 v6, 0xbc000000, v1
	v_mul_f32_e32 v1, v2, v2
	v_fmac_f32_e32 v1, v6, v6
	v_pk_add_f32 v[4:5], v[4:5], v[0:1] op_sel_hi:[1,0] neg_lo:[0,1] neg_hi:[0,1]
	s_nop 0
	v_pk_mul_f32 v[8:9], v[4:5], v[4:5]
	s_nop 0
	v_add_f32_e32 v1, v9, v1
	v_add_f32_e32 v1, v8, v1
	v_mov_b32_e32 v8, v26
	v_mov_b32_e32 v9, v14
	v_pk_add_f32 v[8:9], v[8:9], v[0:1] op_sel_hi:[1,0] neg_lo:[0,1] neg_hi:[0,1]
	s_nop 0
	v_pk_mul_f32 v[12:13], v[8:9], v[8:9]
	s_nop 0
	v_add_f32_e32 v1, v13, v1
	v_add_f32_e32 v14, v12, v1
	v_mov_b32_e32 v12, v22
	v_mov_b32_e32 v13, v10
	v_pk_add_f32 v[0:1], v[12:13], v[0:1] op_sel_hi:[1,0] neg_lo:[0,1] neg_hi:[0,1]
	s_nop 0
	v_pk_mul_f32 v[12:13], v[0:1], v[0:1]
	s_nop 0
	v_add_f32_e32 v10, v13, v14
	v_add_f32_e32 v10, v12, v10
	v_mov_b32_e32 v14, v27
	s_nop 0
	v_add_f32_dpp v10, v10, v10 quad_perm:[1,0,3,2] row_mask:0xf bank_mask:0xf bound_ctrl:1
	s_nop 1
	v_add_f32_dpp v10, v10, v10 quad_perm:[2,3,0,1] row_mask:0xf bank_mask:0xf bound_ctrl:1
	s_nop 1
	v_add_f32_dpp v10, v10, v10 row_half_mirror row_mask:0xf bank_mask:0xf bound_ctrl:1
	s_nop 1
	v_add_f32_dpp v10, v10, v10 row_mirror row_mask:0xf bank_mask:0xf bound_ctrl:1
	v_fmamk_f32 v10, v10, 0x3c000000, v237
	v_cmp_gt_f32_e32 vcc, s74, v10
	v_mul_f32_e32 v12, 0x4b800000, v10
	s_nop 0
	v_cndmask_b32_e32 v10, v10, v12, vcc
	v_rsq_f32_e32 v10, v10
	s_nop 0
	v_mul_f32_e32 v12, 0x45800000, v10
	v_cndmask_b32_e32 v10, v10, v12, vcc
	v_mul_f32_e32 v6, v6, v10
	v_mul_f32_e32 v2, v2, v10
	v_mul_f32_e32 v6, v39, v6
	v_mul_f32_e32 v2, v38, v2
	v_cvt_pk_bf16_f32 v6, v6, v145
	ds_write_b16 v60, v6 offset:544
	v_cvt_pk_bf16_f32 v2, v2, v145
	ds_write_b16 v60, v2 offset:576
	v_mul_f32_e32 v2, v5, v10
	v_mul_f32_e32 v2, v37, v2
	v_cvt_pk_bf16_f32 v2, v2, v145
	ds_write_b16 v60, v2 offset:608
	v_mul_f32_e32 v2, v4, v10
	v_mul_f32_e32 v2, v36, v2
	v_cvt_pk_bf16_f32 v2, v2, v145
	ds_write_b16 v60, v2 offset:640
	v_mul_f32_e32 v2, v9, v10
	v_mul_f32_e32 v2, v35, v2
	v_cvt_pk_bf16_f32 v2, v2, v145
	ds_write_b16 v60, v2 offset:672
	v_mul_f32_e32 v2, v8, v10
	v_mul_f32_e32 v1, v1, v10
	v_mul_f32_e32 v0, v0, v10
	v_mul_f32_e32 v2, v34, v2
	v_mul_f32_e32 v1, v33, v1
	v_mul_f32_e32 v0, v32, v0
	v_cvt_pk_bf16_f32 v2, v2, v145
	ds_write_b16 v60, v2 offset:704
	v_cvt_pk_bf16_f32 v1, v1, v145
	ds_write_b16 v60, v1 offset:736
	v_cvt_pk_bf16_f32 v0, v0, v145
	ds_write_b16 v60, v0 offset:768
	v_add_f32_e32 v0, 0, v7
	v_add_f32_e32 v0, v3, v0
	v_add_f32_e32 v0, v19, v0
	v_add_f32_e32 v0, v31, v0
	v_add_f32_e32 v0, v15, v0
	v_add_f32_e32 v0, v27, v0
	v_add_f32_e32 v0, v11, v0
	v_add_f32_e32 v0, v23, v0
	v_mov_b32_e32 v10, v23
	s_nop 0
	v_add_f32_dpp v0, v0, v0 quad_perm:[1,0,3,2] row_mask:0xf bank_mask:0xf bound_ctrl:1
	s_nop 1
	v_add_f32_dpp v0, v0, v0 quad_perm:[2,3,0,1] row_mask:0xf bank_mask:0xf bound_ctrl:1
	s_nop 1
	v_add_f32_dpp v0, v0, v0 row_half_mirror row_mask:0xf bank_mask:0xf bound_ctrl:1
	s_nop 1
	v_add_f32_dpp v1, v0, v0 row_mirror row_mask:0xf bank_mask:0xf bound_ctrl:1
	v_fmac_f32_e32 v3, 0xbc000000, v1
	v_mul_f32_e32 v0, 0x3c000000, v1
	v_fmac_f32_e32 v7, 0xbc000000, v1
	v_mul_f32_e32 v1, v3, v3
	v_fmac_f32_e32 v1, v7, v7
	v_pk_add_f32 v[4:5], v[18:19], v[0:1] op_sel_hi:[1,0] neg_lo:[0,1] neg_hi:[0,1]
	s_nop 0
	v_pk_mul_f32 v[8:9], v[4:5], v[4:5]
	s_nop 0
	v_add_f32_e32 v1, v9, v1
	v_add_f32_e32 v1, v8, v1
	v_pk_add_f32 v[8:9], v[14:15], v[0:1] op_sel_hi:[1,0] neg_lo:[0,1] neg_hi:[0,1]
	s_nop 0
	v_pk_mul_f32 v[12:13], v[8:9], v[8:9]
	s_nop 0
	v_add_f32_e32 v1, v13, v1
	v_add_f32_e32 v2, v12, v1
	v_pk_add_f32 v[0:1], v[10:11], v[0:1] op_sel_hi:[1,0] neg_lo:[0,1] neg_hi:[0,1]
	s_nop 0
	v_pk_mul_f32 v[10:11], v[0:1], v[0:1]
	s_nop 0
	v_add_f32_e32 v2, v11, v2
	v_add_f32_e32 v2, v10, v2
	s_nop 1
	v_add_f32_dpp v2, v2, v2 quad_perm:[1,0,3,2] row_mask:0xf bank_mask:0xf bound_ctrl:1
	s_nop 1
	v_add_f32_dpp v2, v2, v2 quad_perm:[2,3,0,1] row_mask:0xf bank_mask:0xf bound_ctrl:1
	s_nop 1
	v_add_f32_dpp v2, v2, v2 row_half_mirror row_mask:0xf bank_mask:0xf bound_ctrl:1
	s_nop 1
	v_add_f32_dpp v2, v2, v2 row_mirror row_mask:0xf bank_mask:0xf bound_ctrl:1
	v_fmamk_f32 v2, v2, 0x3c000000, v237
	v_cmp_gt_f32_e32 vcc, s74, v2
	v_mul_f32_e32 v6, 0x4b800000, v2
	s_nop 0
	v_cndmask_b32_e32 v2, v2, v6, vcc
	v_rsq_f32_e32 v2, v2
	s_nop 0
	v_mul_f32_e32 v6, 0x45800000, v2
	v_cndmask_b32_e32 v2, v2, v6, vcc
	v_mul_f32_e32 v6, v7, v2
	v_mul_f32_e32 v3, v3, v2
	v_mul_f32_e32 v6, v39, v6
	v_mul_f32_e32 v3, v38, v3
	v_cvt_pk_bf16_f32 v6, v6, v145
	ds_write_b16 v60, v6 offset:816
	v_cvt_pk_bf16_f32 v3, v3, v145
	ds_write_b16 v60, v3 offset:848
	v_mul_f32_e32 v3, v5, v2
	v_mul_f32_e32 v3, v37, v3
	v_cvt_pk_bf16_f32 v3, v3, v145
	ds_write_b16 v60, v3 offset:880
	v_mul_f32_e32 v3, v4, v2
	v_mul_f32_e32 v3, v36, v3
	v_cvt_pk_bf16_f32 v3, v3, v145
	ds_write_b16 v60, v3 offset:912
	v_mul_f32_e32 v3, v9, v2
	v_mul_f32_e32 v3, v35, v3
	v_cvt_pk_bf16_f32 v3, v3, v145
	ds_write_b16 v60, v3 offset:944
	v_mul_f32_e32 v3, v8, v2
	v_mul_f32_e32 v1, v1, v2
	v_mul_f32_e32 v0, v0, v2
	v_mul_f32_e32 v3, v34, v3
	v_mul_f32_e32 v1, v33, v1
	v_mul_f32_e32 v0, v32, v0
	v_or_b32_e32 v4, v70, v85
	v_cvt_pk_bf16_f32 v3, v3, v145
	ds_write_b16 v60, v3 offset:976
	v_cvt_pk_bf16_f32 v1, v1, v145
	ds_write_b16 v60, v1 offset:1008
	v_cvt_pk_bf16_f32 v0, v0, v145
	ds_write_b16 v60, v0 offset:1040
	v_add_u32_e32 v2, s27, v4
	v_ashrrev_i32_e32 v177, 31, v2
	v_mov_b32_e32 v176, v2
	v_mov_b64_e32 v[178:179], s[10:11]
	v_mad_i64_i32 v[176:177], vcc, v176, s62, v[178:179]
	v_lshl_add_u64 v[176:177], v[176:177], 0, s[80:81]
	v_lshl_add_u64 v[176:177], v[176:177], 0, v[144:145]
	v_add_co_u32_e32 v176, vcc, s76, v176
	s_nop 1
	v_addc_co_u32_e32 v177, vcc, 0, v177, vcc
	s_mov_b64 vcc, 0x10800
	v_lshl_add_u64 v[178:179], v[176:177], 0, vcc
	v_lshl_add_u64 v[180:181], v[178:179], 0, vcc
	v_lshl_add_u64 v[182:183], v[180:181], 0, vcc
	global_load_dwordx4 v[160:163], v[176:177], off offset:1024
	global_load_dwordx4 v[164:167], v[178:179], off offset:1024
	global_load_dwordx4 v[168:171], v[180:181], off offset:1024
	global_load_dwordx4 v[172:175], v[182:183], off offset:1024
	v_mul_lo_u32 v4, v4, s65
	s_waitcnt lgkmcnt(0)
	v_add3_u32 v8, 0, v144, v4
	ds_read_b128 v[10:13], v8
	v_mov_b64_e32 v[4:5], s[10:11]
	v_lshl_add_u64 v[0:1], s[0:1], 0, v[144:145]
	v_ashrrev_i32_e32 v3, 31, v2
	s_waitcnt lgkmcnt(0)
	v_lshlrev_b32_e32 v16, 16, v10
	v_and_b32_e32 v17, 0xffff0000, v10
	v_lshlrev_b32_e32 v20, 16, v12
	v_and_b32_e32 v10, 0xffff0000, v12
	v_lshlrev_b32_e32 v7, 16, v13
	v_and_b32_e32 v6, 0xffff0000, v13
	v_mad_i64_i32 v[12:13], s[0:1], v2, s62, v[4:5]
	v_lshl_add_u64 v[12:13], v[12:13], 0, s[80:81]
	v_lshl_add_u64 v[12:13], v[12:13], 0, v[144:145]
	v_add_co_u32_e32 v12, vcc, s76, v12
	v_lshlrev_b32_e32 v18, 16, v11
	s_nop 0
	v_addc_co_u32_e32 v13, vcc, 0, v13, vcc
	v_and_b32_e32 v19, 0xffff0000, v11
	s_waitcnt vmcnt(3)
	v_lshlrev_b32_e32 v11, 16, v160
	v_and_b32_e32 v21, 0xffff0000, v160
	v_lshlrev_b32_e32 v12, 16, v163
	v_and_b32_e32 v9, 0xffff0000, v163
	v_mul_f32_e32 v15, 0xbfb8aa3b, v11
	v_exp_f32_e32 v15, v15
	v_lshlrev_b32_e32 v22, 16, v161
	v_and_b32_e32 v13, 0xffff0000, v161
	v_lshlrev_b32_e32 v23, 16, v162
	v_add_f32_e32 v15, 1.0, v15
	v_div_scale_f32 v24, s[0:1], v15, v15, v11
	v_rcp_f32_e32 v25, v24
	v_and_b32_e32 v14, 0xffff0000, v162
	v_fma_f32 v26, -v24, v25, 1.0
	v_fmac_f32_e32 v25, v26, v25
	v_div_scale_f32 v26, vcc, v11, v15, v11
	v_mul_f32_e32 v27, v26, v25
	v_fma_f32 v28, -v24, v27, v26
	v_fmac_f32_e32 v27, v28, v25
	v_fma_f32 v24, -v24, v27, v26
	v_div_fmas_f32 v24, v24, v25, v27
	v_div_fixup_f32 v11, v24, v15, v11
	v_mul_f32_e32 v15, 0xbfb8aa3b, v21
	v_exp_f32_e32 v15, v15
	v_mul_f32_e32 v11, v11, v16
	v_add_f32_e32 v15, 1.0, v15
	v_div_scale_f32 v16, s[0:1], v15, v15, v21
	v_rcp_f32_e32 v24, v16
	s_nop 0
	v_fma_f32 v25, -v16, v24, 1.0
	v_fmac_f32_e32 v24, v25, v24
	v_div_scale_f32 v25, vcc, v21, v15, v21
	v_mul_f32_e32 v26, v25, v24
	v_fma_f32 v27, -v16, v26, v25
	v_fmac_f32_e32 v26, v27, v24
	v_fma_f32 v16, -v16, v26, v25
	v_div_fmas_f32 v16, v16, v24, v26
	v_div_fixup_f32 v15, v16, v15, v21
	v_mul_f32_e32 v16, 0xbfb8aa3b, v22
	v_exp_f32_e32 v16, v16
	v_mul_f32_e32 v15, v15, v17
	v_add_f32_e32 v16, 1.0, v16
	v_div_scale_f32 v17, s[0:1], v16, v16, v22
	v_rcp_f32_e32 v21, v17
	s_nop 0
	v_fma_f32 v24, -v17, v21, 1.0
	v_fmac_f32_e32 v21, v24, v21
	v_div_scale_f32 v24, vcc, v22, v16, v22
	v_mul_f32_e32 v25, v24, v21
	v_fma_f32 v26, -v17, v25, v24
	v_fmac_f32_e32 v25, v26, v21
	v_fma_f32 v17, -v17, v25, v24
	v_div_fmas_f32 v17, v17, v21, v25
	v_div_fixup_f32 v16, v17, v16, v22
	v_mul_f32_e32 v17, 0xbfb8aa3b, v13
	v_exp_f32_e32 v17, v17
	v_mul_f32_e32 v16, v16, v18
	v_add_f32_e32 v17, 1.0, v17
	v_div_scale_f32 v18, s[0:1], v17, v17, v13
	v_rcp_f32_e32 v21, v18
	s_nop 0
	v_fma_f32 v22, -v18, v21, 1.0
	v_fmac_f32_e32 v21, v22, v21
	v_div_scale_f32 v22, vcc, v13, v17, v13
	v_mul_f32_e32 v24, v22, v21
	v_fma_f32 v25, -v18, v24, v22
	v_fmac_f32_e32 v24, v25, v21
	v_fma_f32 v18, -v18, v24, v22
	v_div_fmas_f32 v18, v18, v21, v24
	v_div_fixup_f32 v13, v18, v17, v13
	v_mul_f32_e32 v17, 0xbfb8aa3b, v23
	v_exp_f32_e32 v17, v17
	v_mul_f32_e32 v13, v13, v19
	v_add_f32_e32 v17, 1.0, v17
	v_div_scale_f32 v18, s[0:1], v17, v17, v23
	v_rcp_f32_e32 v19, v18
	s_nop 0
	v_fma_f32 v21, -v18, v19, 1.0
	v_fmac_f32_e32 v19, v21, v19
	v_div_scale_f32 v21, vcc, v23, v17, v23
	v_mul_f32_e32 v22, v21, v19
	v_fma_f32 v24, -v18, v22, v21
	v_fmac_f32_e32 v22, v24, v19
	v_fma_f32 v18, -v18, v22, v21
	v_div_fmas_f32 v18, v18, v19, v22
	v_div_fixup_f32 v17, v18, v17, v23
	v_mul_f32_e32 v18, 0xbfb8aa3b, v14
	v_exp_f32_e32 v18, v18
	v_mul_f32_e32 v17, v17, v20
	v_add_f32_e32 v18, 1.0, v18
	v_div_scale_f32 v19, s[0:1], v18, v18, v14
	v_rcp_f32_e32 v20, v19
	s_nop 0
	v_fma_f32 v21, -v19, v20, 1.0
	v_fmac_f32_e32 v20, v21, v20
	v_div_scale_f32 v21, vcc, v14, v18, v14
	v_mul_f32_e32 v22, v21, v20
	v_fma_f32 v23, -v19, v22, v21
	v_fmac_f32_e32 v22, v23, v20
	v_fma_f32 v19, -v19, v22, v21
	v_div_fmas_f32 v19, v19, v20, v22
	v_div_fixup_f32 v14, v19, v18, v14
	v_mul_f32_e32 v14, v14, v10
	v_mul_f32_e32 v10, 0xbfb8aa3b, v12
	v_exp_f32_e32 v10, v10
	s_nop 0
	v_add_f32_e32 v10, 1.0, v10
	v_div_scale_f32 v18, s[0:1], v10, v10, v12
	v_rcp_f32_e32 v19, v18
	s_nop 0
	v_fma_f32 v20, -v18, v19, 1.0
	v_fmac_f32_e32 v19, v20, v19
	v_div_scale_f32 v20, vcc, v12, v10, v12
	v_mul_f32_e32 v21, v20, v19
	v_fma_f32 v22, -v18, v21, v20
	v_fmac_f32_e32 v21, v22, v19
	v_fma_f32 v18, -v18, v21, v20
	v_div_fmas_f32 v18, v18, v19, v21
	v_div_fixup_f32 v10, v18, v10, v12
	v_mul_f32_e32 v7, v10, v7
	v_mul_f32_e32 v10, 0xbfb8aa3b, v9
	v_exp_f32_e32 v10, v10
	s_nop 0
	v_add_f32_e32 v10, 1.0, v10
	v_div_scale_f32 v12, s[0:1], v10, v10, v9
	v_rcp_f32_e32 v18, v12
	s_nop 0
	v_fma_f32 v19, -v12, v18, 1.0
	v_fmac_f32_e32 v18, v19, v18
	v_div_scale_f32 v19, vcc, v9, v10, v9
	v_mul_f32_e32 v20, v19, v18
	v_fma_f32 v21, -v12, v20, v19
	v_fmac_f32_e32 v20, v21, v18
	v_fma_f32 v12, -v12, v20, v19
	v_div_fmas_f32 v12, v12, v18, v20
	v_div_fixup_f32 v9, v12, v10, v9
	v_mul_f32_e32 v6, v9, v6
	v_cvt_pk_bf16_f32 v10, v11, v15
	v_cvt_pk_bf16_f32 v11, v16, v13
	v_cvt_pk_bf16_f32 v12, v17, v14
	v_cvt_pk_bf16_f32 v13, v7, v6
	v_lshlrev_b64 v[6:7], 10, v[2:3]
	v_lshl_add_u64 v[6:7], v[0:1], 0, v[6:7]
	global_store_dwordx4 v[6:7], v[10:13], off
	ds_read_b128 v[10:13], v8 offset:1088
	v_add_u32_e32 v6, 4, v2
	v_ashrrev_i32_e32 v7, 31, v6
	s_waitcnt lgkmcnt(0)
	v_lshlrev_b32_e32 v18, 16, v11
	v_and_b32_e32 v19, 0xffff0000, v11
	v_lshlrev_b32_e32 v20, 16, v12
	v_and_b32_e32 v11, 0xffff0000, v12
	v_lshlrev_b32_e32 v9, 16, v13
	v_and_b32_e32 v3, 0xffff0000, v13
	v_mad_i64_i32 v[12:13], s[0:1], v6, s62, v[4:5]
	v_lshl_add_u64 v[12:13], v[12:13], 0, s[80:81]
	v_lshl_add_u64 v[12:13], v[12:13], 0, v[144:145]
	v_add_co_u32_e32 v12, vcc, s76, v12
	v_lshlrev_b32_e32 v16, 16, v10
	s_nop 0
	v_addc_co_u32_e32 v13, vcc, 0, v13, vcc
	v_and_b32_e32 v17, 0xffff0000, v10
	v_lshlrev_b64 v[6:7], 10, v[6:7]
	v_lshl_add_u64 v[6:7], v[0:1], 0, v[6:7]
	s_waitcnt vmcnt(3)
	v_lshlrev_b32_e32 v21, 16, v164
	v_and_b32_e32 v22, 0xffff0000, v164
	v_mul_f32_e32 v12, 0xbfb8aa3b, v21
	v_exp_f32_e32 v12, v12
	v_lshlrev_b32_e32 v23, 16, v165
	v_and_b32_e32 v24, 0xffff0000, v165
	v_lshlrev_b32_e32 v13, 16, v167
	v_add_f32_e32 v12, 1.0, v12
	v_and_b32_e32 v10, 0xffff0000, v167
	v_div_scale_f32 v15, s[0:1], v12, v12, v21
	v_rcp_f32_e32 v26, v15
	v_lshlrev_b32_e32 v25, 16, v166
	v_and_b32_e32 v14, 0xffff0000, v166
	v_fma_f32 v27, -v15, v26, 1.0
	v_fmac_f32_e32 v26, v27, v26
	v_div_scale_f32 v27, vcc, v21, v12, v21
	v_mul_f32_e32 v28, v27, v26
	v_fma_f32 v29, -v15, v28, v27
	v_fmac_f32_e32 v28, v29, v26
	v_fma_f32 v15, -v15, v28, v27
	v_div_fmas_f32 v15, v15, v26, v28
	v_div_fixup_f32 v12, v15, v12, v21
	v_mul_f32_e32 v15, 0xbfb8aa3b, v22
	v_exp_f32_e32 v15, v15
	v_mul_f32_e32 v12, v12, v16
	v_add_f32_e32 v15, 1.0, v15
	v_div_scale_f32 v16, s[0:1], v15, v15, v22
	v_rcp_f32_e32 v21, v16
	s_nop 0
	v_fma_f32 v26, -v16, v21, 1.0
	v_fmac_f32_e32 v21, v26, v21
	v_div_scale_f32 v26, vcc, v22, v15, v22
	v_mul_f32_e32 v27, v26, v21
	v_fma_f32 v28, -v16, v27, v26
	v_fmac_f32_e32 v27, v28, v21
	v_fma_f32 v16, -v16, v27, v26
	v_div_fmas_f32 v16, v16, v21, v27
	v_div_fixup_f32 v15, v16, v15, v22
	v_mul_f32_e32 v16, 0xbfb8aa3b, v23
	v_exp_f32_e32 v16, v16
	v_mul_f32_e32 v15, v15, v17
	v_add_f32_e32 v16, 1.0, v16
	v_div_scale_f32 v17, s[0:1], v16, v16, v23
	v_rcp_f32_e32 v21, v17
	s_nop 0
	v_fma_f32 v22, -v17, v21, 1.0
	v_fmac_f32_e32 v21, v22, v21
	v_div_scale_f32 v22, vcc, v23, v16, v23
	v_mul_f32_e32 v26, v22, v21
	v_fma_f32 v27, -v17, v26, v22
	v_fmac_f32_e32 v26, v27, v21
	v_fma_f32 v17, -v17, v26, v22
	v_div_fmas_f32 v17, v17, v21, v26
	v_div_fixup_f32 v16, v17, v16, v23
	v_mul_f32_e32 v17, 0xbfb8aa3b, v24
	v_exp_f32_e32 v17, v17
	v_mul_f32_e32 v16, v16, v18
	v_add_f32_e32 v17, 1.0, v17
	v_div_scale_f32 v18, s[0:1], v17, v17, v24
	v_rcp_f32_e32 v21, v18
	s_nop 0
	v_fma_f32 v22, -v18, v21, 1.0
	v_fmac_f32_e32 v21, v22, v21
	v_div_scale_f32 v22, vcc, v24, v17, v24
	v_mul_f32_e32 v23, v22, v21
	v_fma_f32 v26, -v18, v23, v22
	v_fmac_f32_e32 v23, v26, v21
	v_fma_f32 v18, -v18, v23, v22
	v_div_fmas_f32 v18, v18, v21, v23
	v_div_fixup_f32 v17, v18, v17, v24
	v_mul_f32_e32 v18, 0xbfb8aa3b, v25
	v_exp_f32_e32 v18, v18
	v_mul_f32_e32 v17, v17, v19
	v_add_f32_e32 v18, 1.0, v18
	v_div_scale_f32 v19, s[0:1], v18, v18, v25
	v_rcp_f32_e32 v21, v19
	s_nop 0
	v_fma_f32 v22, -v19, v21, 1.0
	v_fmac_f32_e32 v21, v22, v21
	v_div_scale_f32 v22, vcc, v25, v18, v25
	v_mul_f32_e32 v23, v22, v21
	v_fma_f32 v24, -v19, v23, v22
	v_fmac_f32_e32 v23, v24, v21
	v_fma_f32 v19, -v19, v23, v22
	v_div_fmas_f32 v19, v19, v21, v23
	v_div_fixup_f32 v18, v19, v18, v25
	v_mul_f32_e32 v19, 0xbfb8aa3b, v14
	v_exp_f32_e32 v19, v19
	v_mul_f32_e32 v18, v18, v20
	v_add_f32_e32 v19, 1.0, v19
	v_div_scale_f32 v20, s[0:1], v19, v19, v14
	v_rcp_f32_e32 v21, v20
	s_nop 0
	v_fma_f32 v22, -v20, v21, 1.0
	v_fmac_f32_e32 v21, v22, v21
	v_div_scale_f32 v22, vcc, v14, v19, v14
	v_mul_f32_e32 v23, v22, v21
	v_fma_f32 v24, -v20, v23, v22
	v_fmac_f32_e32 v23, v24, v21
	v_fma_f32 v20, -v20, v23, v22
	v_div_fmas_f32 v20, v20, v21, v23
	v_div_fixup_f32 v14, v20, v19, v14
	v_mul_f32_e32 v14, v14, v11
	v_mul_f32_e32 v11, 0xbfb8aa3b, v13
	v_exp_f32_e32 v11, v11
	s_nop 0
	v_add_f32_e32 v11, 1.0, v11
	v_div_scale_f32 v19, s[0:1], v11, v11, v13
	v_rcp_f32_e32 v20, v19
	s_nop 0
	v_fma_f32 v21, -v19, v20, 1.0
	v_fmac_f32_e32 v20, v21, v20
	v_div_scale_f32 v21, vcc, v13, v11, v13
	v_mul_f32_e32 v22, v21, v20
	v_fma_f32 v23, -v19, v22, v21
	v_fmac_f32_e32 v22, v23, v20
	v_fma_f32 v19, -v19, v22, v21
	v_div_fmas_f32 v19, v19, v20, v22
	v_div_fixup_f32 v11, v19, v11, v13
	v_mul_f32_e32 v9, v11, v9
	v_mul_f32_e32 v11, 0xbfb8aa3b, v10
	v_exp_f32_e32 v11, v11
	s_nop 0
	v_add_f32_e32 v11, 1.0, v11
	v_div_scale_f32 v13, s[0:1], v11, v11, v10
	v_rcp_f32_e32 v19, v13
	s_nop 0
	v_fma_f32 v20, -v13, v19, 1.0
	v_fmac_f32_e32 v19, v20, v19
	v_div_scale_f32 v20, vcc, v10, v11, v10
	v_mul_f32_e32 v21, v20, v19
	v_fma_f32 v22, -v13, v21, v20
	v_fmac_f32_e32 v21, v22, v19
	v_fma_f32 v13, -v13, v21, v20
	v_div_fmas_f32 v13, v13, v19, v21
	v_div_fixup_f32 v10, v13, v11, v10
	v_mul_f32_e32 v3, v10, v3
	v_cvt_pk_bf16_f32 v10, v12, v15
	v_cvt_pk_bf16_f32 v11, v16, v17
	v_cvt_pk_bf16_f32 v12, v18, v14
	v_cvt_pk_bf16_f32 v13, v9, v3
	global_store_dwordx4 v[6:7], v[10:13], off
	ds_read_b128 v[10:13], v8 offset:2176
	v_add_u32_e32 v6, 8, v2
	v_add_u32_e32 v2, 12, v2
	v_ashrrev_i32_e32 v7, 31, v6
	s_waitcnt lgkmcnt(0)
	v_lshlrev_b32_e32 v18, 16, v11
	v_and_b32_e32 v19, 0xffff0000, v11
	v_lshlrev_b32_e32 v20, 16, v12
	v_and_b32_e32 v11, 0xffff0000, v12
	v_lshlrev_b32_e32 v9, 16, v13
	v_and_b32_e32 v3, 0xffff0000, v13
	v_mad_i64_i32 v[12:13], s[0:1], v6, s62, v[4:5]
	v_lshl_add_u64 v[12:13], v[12:13], 0, s[80:81]
	v_lshl_add_u64 v[12:13], v[12:13], 0, v[144:145]
	v_add_co_u32_e32 v12, vcc, s76, v12
	v_lshlrev_b32_e32 v16, 16, v10
	s_nop 0
	v_addc_co_u32_e32 v13, vcc, 0, v13, vcc
	v_and_b32_e32 v17, 0xffff0000, v10
	v_mad_i64_i32 v[4:5], s[0:1], v2, s62, v[4:5]
	v_lshl_add_u64 v[4:5], v[4:5], 0, s[80:81]
	v_lshlrev_b64 v[6:7], 10, v[6:7]
	v_lshl_add_u64 v[4:5], v[4:5], 0, v[144:145]
	v_lshl_add_u64 v[6:7], v[0:1], 0, v[6:7]
	s_waitcnt vmcnt(3)
	v_lshlrev_b32_e32 v21, 16, v168
	v_and_b32_e32 v22, 0xffff0000, v168
	v_mul_f32_e32 v12, 0xbfb8aa3b, v21
	v_exp_f32_e32 v12, v12
	v_lshlrev_b32_e32 v23, 16, v169
	v_and_b32_e32 v24, 0xffff0000, v169
	v_lshlrev_b32_e32 v13, 16, v171
	v_add_f32_e32 v12, 1.0, v12
	v_and_b32_e32 v10, 0xffff0000, v171
	v_div_scale_f32 v15, s[0:1], v12, v12, v21
	v_rcp_f32_e32 v26, v15
	v_lshlrev_b32_e32 v25, 16, v170
	v_and_b32_e32 v14, 0xffff0000, v170
	v_fma_f32 v27, -v15, v26, 1.0
	v_fmac_f32_e32 v26, v27, v26
	v_div_scale_f32 v27, vcc, v21, v12, v21
	v_mul_f32_e32 v28, v27, v26
	v_fma_f32 v29, -v15, v28, v27
	v_fmac_f32_e32 v28, v29, v26
	v_fma_f32 v15, -v15, v28, v27
	v_div_fmas_f32 v15, v15, v26, v28
	v_div_fixup_f32 v12, v15, v12, v21
	v_mul_f32_e32 v15, 0xbfb8aa3b, v22
	v_exp_f32_e32 v15, v15
	v_mul_f32_e32 v12, v12, v16
	v_add_f32_e32 v15, 1.0, v15
	v_div_scale_f32 v16, s[0:1], v15, v15, v22
	v_rcp_f32_e32 v21, v16
	s_nop 0
	v_fma_f32 v26, -v16, v21, 1.0
	v_fmac_f32_e32 v21, v26, v21
	v_div_scale_f32 v26, vcc, v22, v15, v22
	v_mul_f32_e32 v27, v26, v21
	v_fma_f32 v28, -v16, v27, v26
	v_fmac_f32_e32 v27, v28, v21
	v_fma_f32 v16, -v16, v27, v26
	v_div_fmas_f32 v16, v16, v21, v27
	v_div_fixup_f32 v15, v16, v15, v22
	v_mul_f32_e32 v16, 0xbfb8aa3b, v23
	v_exp_f32_e32 v16, v16
	v_mul_f32_e32 v15, v15, v17
	v_add_f32_e32 v16, 1.0, v16
	v_div_scale_f32 v17, s[0:1], v16, v16, v23
	v_rcp_f32_e32 v21, v17
	s_nop 0
	v_fma_f32 v22, -v17, v21, 1.0
	v_fmac_f32_e32 v21, v22, v21
	v_div_scale_f32 v22, vcc, v23, v16, v23
	v_mul_f32_e32 v26, v22, v21
	v_fma_f32 v27, -v17, v26, v22
	v_fmac_f32_e32 v26, v27, v21
	v_fma_f32 v17, -v17, v26, v22
	v_div_fmas_f32 v17, v17, v21, v26
	v_div_fixup_f32 v16, v17, v16, v23
	v_mul_f32_e32 v17, 0xbfb8aa3b, v24
	v_exp_f32_e32 v17, v17
	v_mul_f32_e32 v16, v16, v18
	v_add_f32_e32 v17, 1.0, v17
	v_div_scale_f32 v18, s[0:1], v17, v17, v24
	v_rcp_f32_e32 v21, v18
	s_nop 0
	v_fma_f32 v22, -v18, v21, 1.0
	v_fmac_f32_e32 v21, v22, v21
	v_div_scale_f32 v22, vcc, v24, v17, v24
	v_mul_f32_e32 v23, v22, v21
	v_fma_f32 v26, -v18, v23, v22
	v_fmac_f32_e32 v23, v26, v21
	v_fma_f32 v18, -v18, v23, v22
	v_div_fmas_f32 v18, v18, v21, v23
	v_div_fixup_f32 v17, v18, v17, v24
	v_mul_f32_e32 v18, 0xbfb8aa3b, v25
	v_exp_f32_e32 v18, v18
	v_mul_f32_e32 v17, v17, v19
	v_add_f32_e32 v18, 1.0, v18
	v_div_scale_f32 v19, s[0:1], v18, v18, v25
	v_rcp_f32_e32 v21, v19
	s_nop 0
	v_fma_f32 v22, -v19, v21, 1.0
	v_fmac_f32_e32 v21, v22, v21
	v_div_scale_f32 v22, vcc, v25, v18, v25
	v_mul_f32_e32 v23, v22, v21
	v_fma_f32 v24, -v19, v23, v22
	v_fmac_f32_e32 v23, v24, v21
	v_fma_f32 v19, -v19, v23, v22
	v_div_fmas_f32 v19, v19, v21, v23
	v_div_fixup_f32 v18, v19, v18, v25
	v_mul_f32_e32 v19, 0xbfb8aa3b, v14
	v_exp_f32_e32 v19, v19
	v_mul_f32_e32 v18, v18, v20
	v_add_f32_e32 v19, 1.0, v19
	v_div_scale_f32 v20, s[0:1], v19, v19, v14
	v_rcp_f32_e32 v21, v20
	s_nop 0
	v_fma_f32 v22, -v20, v21, 1.0
	v_fmac_f32_e32 v21, v22, v21
	v_div_scale_f32 v22, vcc, v14, v19, v14
	v_mul_f32_e32 v23, v22, v21
	v_fma_f32 v24, -v20, v23, v22
	v_fmac_f32_e32 v23, v24, v21
	v_fma_f32 v20, -v20, v23, v22
	v_div_fmas_f32 v20, v20, v21, v23
	v_div_fixup_f32 v14, v20, v19, v14
	v_mul_f32_e32 v14, v14, v11
	v_mul_f32_e32 v11, 0xbfb8aa3b, v13
	v_exp_f32_e32 v11, v11
	s_nop 0
	v_add_f32_e32 v11, 1.0, v11
	v_div_scale_f32 v19, s[0:1], v11, v11, v13
	v_rcp_f32_e32 v20, v19
	s_nop 0
	v_fma_f32 v21, -v19, v20, 1.0
	v_fmac_f32_e32 v20, v21, v20
	v_div_scale_f32 v21, vcc, v13, v11, v13
	v_mul_f32_e32 v22, v21, v20
	v_fma_f32 v23, -v19, v22, v21
	v_fmac_f32_e32 v22, v23, v20
	v_fma_f32 v19, -v19, v22, v21
	v_div_fmas_f32 v19, v19, v20, v22
	v_div_fixup_f32 v11, v19, v11, v13
	v_mul_f32_e32 v9, v11, v9
	v_mul_f32_e32 v11, 0xbfb8aa3b, v10
	v_exp_f32_e32 v11, v11
	s_nop 0
	v_add_f32_e32 v11, 1.0, v11
	v_div_scale_f32 v13, s[0:1], v11, v11, v10
	v_rcp_f32_e32 v19, v13
	s_nop 0
	v_fma_f32 v20, -v13, v19, 1.0
	v_fmac_f32_e32 v19, v20, v19
	v_div_scale_f32 v20, vcc, v10, v11, v10
	v_mul_f32_e32 v21, v20, v19
	v_fma_f32 v22, -v13, v21, v20
	v_fmac_f32_e32 v21, v22, v19
	v_fma_f32 v13, -v13, v21, v20
	v_div_fmas_f32 v13, v13, v19, v21
	v_div_fixup_f32 v10, v13, v11, v10
	v_add_co_u32_e32 v4, vcc, s76, v4
	v_mul_f32_e32 v3, v10, v3
	v_cvt_pk_bf16_f32 v10, v12, v15
	v_cvt_pk_bf16_f32 v11, v16, v17
	v_cvt_pk_bf16_f32 v12, v18, v14
	v_cvt_pk_bf16_f32 v13, v9, v3
	global_store_dwordx4 v[6:7], v[10:13], off
	v_addc_co_u32_e32 v5, vcc, 0, v5, vcc
	ds_read_b128 v[6:9], v8 offset:3264
	v_ashrrev_i32_e32 v3, 31, v2
	v_lshlrev_b64 v[2:3], 10, v[2:3]
	v_lshl_add_u64 v[0:1], v[0:1], 0, v[2:3]
	s_waitcnt lgkmcnt(0)
	v_lshlrev_b32_e32 v14, 16, v6
	v_and_b32_e32 v15, 0xffff0000, v6
	v_lshlrev_b32_e32 v16, 16, v7
	v_and_b32_e32 v17, 0xffff0000, v7
	v_lshlrev_b32_e32 v7, 16, v9
	v_and_b32_e32 v6, 0xffff0000, v9
	v_lshlrev_b32_e32 v18, 16, v8
	v_and_b32_e32 v8, 0xffff0000, v8
	s_waitcnt vmcnt(3)
	v_lshlrev_b32_e32 v5, 16, v172
	v_lshlrev_b32_e32 v9, 16, v175
	v_and_b32_e32 v4, 0xffff0000, v175
	v_mul_f32_e32 v13, 0xbfb8aa3b, v5
	v_exp_f32_e32 v13, v13
	v_and_b32_e32 v10, 0xffff0000, v172
	v_lshlrev_b32_e32 v19, 16, v173
	v_and_b32_e32 v11, 0xffff0000, v173
	v_add_f32_e32 v13, 1.0, v13
	v_div_scale_f32 v21, s[0:1], v13, v13, v5
	v_rcp_f32_e32 v22, v21
	v_lshlrev_b32_e32 v20, 16, v174
	v_and_b32_e32 v12, 0xffff0000, v174
	v_fma_f32 v23, -v21, v22, 1.0
	v_fmac_f32_e32 v22, v23, v22
	v_div_scale_f32 v23, vcc, v5, v13, v5
	v_mul_f32_e32 v24, v23, v22
	v_fma_f32 v25, -v21, v24, v23
	v_fmac_f32_e32 v24, v25, v22
	v_fma_f32 v21, -v21, v24, v23
	v_div_fmas_f32 v21, v21, v22, v24
	v_div_fixup_f32 v5, v21, v13, v5
	v_mul_f32_e32 v13, 0xbfb8aa3b, v10
	v_exp_f32_e32 v13, v13
	v_mul_f32_e32 v5, v5, v14
	v_add_f32_e32 v13, 1.0, v13
	v_div_scale_f32 v14, s[0:1], v13, v13, v10
	v_rcp_f32_e32 v21, v14
	s_nop 0
	v_fma_f32 v22, -v14, v21, 1.0
	v_fmac_f32_e32 v21, v22, v21
	v_div_scale_f32 v22, vcc, v10, v13, v10
	v_mul_f32_e32 v23, v22, v21
	v_fma_f32 v24, -v14, v23, v22
	v_fmac_f32_e32 v23, v24, v21
	v_fma_f32 v14, -v14, v23, v22
	v_div_fmas_f32 v14, v14, v21, v23
	v_div_fixup_f32 v10, v14, v13, v10
	v_mul_f32_e32 v13, 0xbfb8aa3b, v19
	v_exp_f32_e32 v13, v13
	v_mul_f32_e32 v10, v10, v15
	v_add_f32_e32 v13, 1.0, v13
	v_div_scale_f32 v14, s[0:1], v13, v13, v19
	v_rcp_f32_e32 v15, v14
	s_nop 0
	v_fma_f32 v21, -v14, v15, 1.0
	v_fmac_f32_e32 v15, v21, v15
	v_div_scale_f32 v21, vcc, v19, v13, v19
	v_mul_f32_e32 v22, v21, v15
	v_fma_f32 v23, -v14, v22, v21
	v_fmac_f32_e32 v22, v23, v15
	v_fma_f32 v14, -v14, v22, v21
	v_div_fmas_f32 v14, v14, v15, v22
	v_div_fixup_f32 v13, v14, v13, v19
	v_mul_f32_e32 v14, 0xbfb8aa3b, v11
	v_exp_f32_e32 v14, v14
	v_mul_f32_e32 v13, v13, v16
	v_add_f32_e32 v14, 1.0, v14
	v_div_scale_f32 v15, s[0:1], v14, v14, v11
	v_rcp_f32_e32 v16, v15
	s_nop 0
	v_fma_f32 v19, -v15, v16, 1.0
	v_fmac_f32_e32 v16, v19, v16
	v_div_scale_f32 v19, vcc, v11, v14, v11
	v_mul_f32_e32 v21, v19, v16
	v_fma_f32 v22, -v15, v21, v19
	v_fmac_f32_e32 v21, v22, v16
	v_fma_f32 v15, -v15, v21, v19
	v_div_fmas_f32 v15, v15, v16, v21
	v_div_fixup_f32 v11, v15, v14, v11
	v_mul_f32_e32 v14, 0xbfb8aa3b, v20
	v_exp_f32_e32 v14, v14
	v_mul_f32_e32 v11, v11, v17
	v_add_f32_e32 v14, 1.0, v14
	v_div_scale_f32 v15, s[0:1], v14, v14, v20
	v_rcp_f32_e32 v16, v15
	s_nop 0
	v_fma_f32 v17, -v15, v16, 1.0
	v_fmac_f32_e32 v16, v17, v16
	v_div_scale_f32 v17, vcc, v20, v14, v20
	v_mul_f32_e32 v19, v17, v16
	v_fma_f32 v21, -v15, v19, v17
	v_fmac_f32_e32 v19, v21, v16
	v_fma_f32 v15, -v15, v19, v17
	v_div_fmas_f32 v15, v15, v16, v19
	v_div_fixup_f32 v14, v15, v14, v20
	v_mul_f32_e32 v15, 0xbfb8aa3b, v12
	v_exp_f32_e32 v15, v15
	v_mul_f32_e32 v14, v14, v18
	v_add_f32_e32 v15, 1.0, v15
	v_div_scale_f32 v16, s[0:1], v15, v15, v12
	v_rcp_f32_e32 v17, v16
	s_nop 0
	v_fma_f32 v18, -v16, v17, 1.0
	v_fmac_f32_e32 v17, v18, v17
	v_div_scale_f32 v18, vcc, v12, v15, v12
	v_mul_f32_e32 v19, v18, v17
	v_fma_f32 v20, -v16, v19, v18
	v_fmac_f32_e32 v19, v20, v17
	v_fma_f32 v16, -v16, v19, v18
	v_div_fmas_f32 v16, v16, v17, v19
	v_div_fixup_f32 v12, v16, v15, v12
	v_mul_f32_e32 v8, v12, v8
	v_mul_f32_e32 v12, 0xbfb8aa3b, v9
	v_exp_f32_e32 v12, v12
	s_nop 0
	v_add_f32_e32 v12, 1.0, v12
	v_div_scale_f32 v15, s[0:1], v12, v12, v9
	v_rcp_f32_e32 v16, v15
	s_nop 0
	v_fma_f32 v17, -v15, v16, 1.0
	v_fmac_f32_e32 v16, v17, v16
	v_div_scale_f32 v17, vcc, v9, v12, v9
	v_mul_f32_e32 v18, v17, v16
	v_fma_f32 v19, -v15, v18, v17
	v_fmac_f32_e32 v18, v19, v16
	v_fma_f32 v15, -v15, v18, v17
	v_div_fmas_f32 v15, v15, v16, v18
	v_div_fixup_f32 v9, v15, v12, v9
	v_mul_f32_e32 v7, v9, v7
	v_mul_f32_e32 v9, 0xbfb8aa3b, v4
	v_exp_f32_e32 v9, v9
	s_nop 0
	v_add_f32_e32 v9, 1.0, v9
	v_div_scale_f32 v12, s[0:1], v9, v9, v4
	v_rcp_f32_e32 v15, v12
	s_nop 0
	v_fma_f32 v16, -v12, v15, 1.0
	v_fmac_f32_e32 v15, v16, v15
	v_div_scale_f32 v16, vcc, v4, v9, v4
	v_mul_f32_e32 v17, v16, v15
	v_fma_f32 v18, -v12, v17, v16
	v_fmac_f32_e32 v17, v18, v15
	v_fma_f32 v12, -v12, v17, v16
	v_div_fmas_f32 v12, v12, v15, v17
	v_div_fixup_f32 v4, v12, v9, v4
	v_mul_f32_e32 v9, v4, v6
	v_cvt_pk_bf16_f32 v4, v5, v10
	v_cvt_pk_bf16_f32 v5, v13, v11
	v_cvt_pk_bf16_f32 v6, v14, v8
	v_cvt_pk_bf16_f32 v7, v7, v9
	global_store_dwordx4 v[0:1], v[4:7], off
	s_barrier
	s_cbranch_scc1 .LBB0_894
